# top-k radix select: the four ballots of each step use separate SGPR pairs so VALU-to-SALU latencies overlap
# speedup vs baseline: 1.0127x; 1.0002x over previous
.LBB0_573:
	v_mov_b32_e32 v4, v3
	s_and_saveexec_b64 s[88:89], vcc
	s_cbranch_execz .LBB0_577
	v_add_u32_e32 v10, s84, v105
	ds_read2st64_b32 v[6:7], v10 offset1:1
	ds_read2st64_b32 v[8:9], v10 offset0:16 offset1:17
	s_waitcnt lgkmcnt(0)
	v_add_f32_e32 v4, v6, v8
	v_max_f32_e32 v4, 0, v4
	v_add_u32_e32 v4, 1, v4
	v_cndmask_b32_e64 v5, v4, 0, s[86:87]
	v_add_f32_e32 v4, v7, v9
	ds_read2st64_b32 v[6:7], v10 offset0:2 offset1:3
	ds_read2st64_b32 v[8:9], v10 offset0:18 offset1:19
	v_max_f32_e32 v4, 0, v4
	v_add_u32_e32 v4, 1, v4
	v_cndmask_b32_e64 v4, v4, 0, s[60:61]
	v_cmp_lt_u32_e64 s[66:67], s16, v5
	s_waitcnt lgkmcnt(0)
	v_add_f32_e32 v6, v6, v8
	v_max_f32_e32 v6, 0, v6
	v_add_f32_e32 v7, v7, v9
	v_add_u32_e32 v6, 1, v6
	v_max_f32_e32 v7, 0, v7
	v_cndmask_b32_e64 v6, v6, 0, s[62:63]
	v_add_u32_e32 v7, 1, v7
	s_bcnt1_i32_b64 s2, s[66:67]
	v_cmp_lt_u32_e64 s[66:67], s16, v4
	v_cndmask_b32_e64 v7, v7, 0, s[64:65]
	s_bcnt1_i32_b64 s3, s[66:67]
	v_cmp_lt_u32_e64 s[66:67], s16, v6
	s_add_i32 s2, s3, s2
	s_bcnt1_i32_b64 s3, s[66:67]
	v_cmp_lt_u32_e64 s[66:67], s16, v7
	s_add_i32 s2, s2, s3
	s_bcnt1_i32_b64 s3, s[66:67]
	s_add_i32 s2, s2, s3
	s_cmp_gt_u32 s2, 12
	s_cselect_b32 s2, 2.0, 0
	s_or_b32 s3, s2, 0x20000000
	v_cmp_le_u32_e64 s[66:67], s3, v5
	v_cmp_le_u32_e64 s[70:71], s3, v4
	v_cmp_le_u32_e64 s[72:73], s3, v6
	v_cmp_le_u32_e64 s[74:75], s3, v7
	s_bcnt1_i32_b64 s68, s[66:67]
	s_bcnt1_i32_b64 s66, s[70:71]
	s_add_i32 s68, s66, s68
	s_bcnt1_i32_b64 s66, s[72:73]
	s_add_i32 s68, s68, s66
	s_bcnt1_i32_b64 s66, s[74:75]
	s_add_i32 s68, s68, s66
	s_cmp_gt_u32 s68, 12
	s_cselect_b32 s2, s3, s2
	s_cmp_eq_u32 s68, 13
	s_cbranch_scc1 .Ltopk_early
	s_or_b32 s3, s2, 0x10000000
	v_cmp_le_u32_e64 s[66:67], s3, v5
	v_cmp_le_u32_e64 s[70:71], s3, v4
	v_cmp_le_u32_e64 s[72:73], s3, v6
	v_cmp_le_u32_e64 s[74:75], s3, v7
	s_bcnt1_i32_b64 s68, s[66:67]
	s_bcnt1_i32_b64 s66, s[70:71]
	s_add_i32 s68, s66, s68
	s_bcnt1_i32_b64 s66, s[72:73]
	s_add_i32 s68, s68, s66
	s_bcnt1_i32_b64 s66, s[74:75]
	s_add_i32 s68, s68, s66
	s_cmp_gt_u32 s68, 12
	s_cselect_b32 s2, s3, s2
	s_cmp_eq_u32 s68, 13
	s_cbranch_scc1 .Ltopk_early
	s_or_b32 s3, s2, 0x8000000
	v_cmp_le_u32_e64 s[66:67], s3, v5
	v_cmp_le_u32_e64 s[70:71], s3, v4
	v_cmp_le_u32_e64 s[72:73], s3, v6
	v_cmp_le_u32_e64 s[74:75], s3, v7
	s_bcnt1_i32_b64 s68, s[66:67]
	s_bcnt1_i32_b64 s66, s[70:71]
	s_add_i32 s68, s66, s68
	s_bcnt1_i32_b64 s66, s[72:73]
	s_add_i32 s68, s68, s66
	s_bcnt1_i32_b64 s66, s[74:75]
	s_add_i32 s68, s68, s66
	s_cmp_gt_u32 s68, 12
	s_cselect_b32 s2, s3, s2
	s_cmp_eq_u32 s68, 13
	s_cbranch_scc1 .Ltopk_early
	s_or_b32 s3, s2, 0x4000000
	v_cmp_le_u32_e64 s[66:67], s3, v5
	v_cmp_le_u32_e64 s[70:71], s3, v4
	v_cmp_le_u32_e64 s[72:73], s3, v6
	v_cmp_le_u32_e64 s[74:75], s3, v7
	s_bcnt1_i32_b64 s68, s[66:67]
	s_bcnt1_i32_b64 s66, s[70:71]
	s_add_i32 s68, s66, s68
	s_bcnt1_i32_b64 s66, s[72:73]
	s_add_i32 s68, s68, s66
	s_bcnt1_i32_b64 s66, s[74:75]
	s_add_i32 s68, s68, s66
	s_cmp_gt_u32 s68, 12
	s_cselect_b32 s2, s3, s2
	s_cmp_eq_u32 s68, 13
	s_cbranch_scc1 .Ltopk_early
	s_or_b32 s3, s2, 0x2000000
	v_cmp_le_u32_e64 s[66:67], s3, v5
	v_cmp_le_u32_e64 s[70:71], s3, v4
	v_cmp_le_u32_e64 s[72:73], s3, v6
	v_cmp_le_u32_e64 s[74:75], s3, v7
	s_bcnt1_i32_b64 s68, s[66:67]
	s_bcnt1_i32_b64 s66, s[70:71]
	s_add_i32 s68, s66, s68
	s_bcnt1_i32_b64 s66, s[72:73]
	s_add_i32 s68, s68, s66
	s_bcnt1_i32_b64 s66, s[74:75]
	s_add_i32 s68, s68, s66
	s_cmp_gt_u32 s68, 12
	s_cselect_b32 s2, s3, s2
	s_cmp_eq_u32 s68, 13
	s_cbranch_scc1 .Ltopk_early
	s_or_b32 s3, s2, 0x1000000
	v_cmp_le_u32_e64 s[66:67], s3, v5
	v_cmp_le_u32_e64 s[70:71], s3, v4
	v_cmp_le_u32_e64 s[72:73], s3, v6
	v_cmp_le_u32_e64 s[74:75], s3, v7
	s_bcnt1_i32_b64 s68, s[66:67]
	s_bcnt1_i32_b64 s66, s[70:71]
	s_add_i32 s68, s66, s68
	s_bcnt1_i32_b64 s66, s[72:73]
	s_add_i32 s68, s68, s66
	s_bcnt1_i32_b64 s66, s[74:75]
	s_add_i32 s68, s68, s66
	s_cmp_gt_u32 s68, 12
	s_cselect_b32 s2, s3, s2
	s_cmp_eq_u32 s68, 13
	s_cbranch_scc1 .Ltopk_early
	s_or_b32 s3, s2, 0x800000
	v_cmp_le_u32_e64 s[66:67], s3, v5
	v_cmp_le_u32_e64 s[70:71], s3, v4
	v_cmp_le_u32_e64 s[72:73], s3, v6
	v_cmp_le_u32_e64 s[74:75], s3, v7
	s_bcnt1_i32_b64 s68, s[66:67]
	s_bcnt1_i32_b64 s66, s[70:71]
	s_add_i32 s68, s66, s68
	s_bcnt1_i32_b64 s66, s[72:73]
	s_add_i32 s68, s68, s66
	s_bcnt1_i32_b64 s66, s[74:75]
	s_add_i32 s68, s68, s66
	s_cmp_gt_u32 s68, 12
	s_cselect_b32 s2, s3, s2
	s_cmp_eq_u32 s68, 13
	s_cbranch_scc1 .Ltopk_early
	s_or_b32 s3, s2, 0x400000
	v_cmp_le_u32_e64 s[66:67], s3, v5
	v_cmp_le_u32_e64 s[70:71], s3, v4
	v_cmp_le_u32_e64 s[72:73], s3, v6
	v_cmp_le_u32_e64 s[74:75], s3, v7
	s_bcnt1_i32_b64 s68, s[66:67]
	s_bcnt1_i32_b64 s66, s[70:71]
	s_add_i32 s68, s66, s68
	s_bcnt1_i32_b64 s66, s[72:73]
	s_add_i32 s68, s68, s66
	s_bcnt1_i32_b64 s66, s[74:75]
	s_add_i32 s68, s68, s66
	s_cmp_gt_u32 s68, 12
	s_cselect_b32 s2, s3, s2
	s_cmp_eq_u32 s68, 13
	s_cbranch_scc1 .Ltopk_early
	s_or_b32 s3, s2, 0x200000
	v_cmp_le_u32_e64 s[66:67], s3, v5
	v_cmp_le_u32_e64 s[70:71], s3, v4
	v_cmp_le_u32_e64 s[72:73], s3, v6
	v_cmp_le_u32_e64 s[74:75], s3, v7
	s_bcnt1_i32_b64 s68, s[66:67]
	s_bcnt1_i32_b64 s66, s[70:71]
	s_add_i32 s68, s66, s68
	s_bcnt1_i32_b64 s66, s[72:73]
	s_add_i32 s68, s68, s66
	s_bcnt1_i32_b64 s66, s[74:75]
	s_add_i32 s68, s68, s66
	s_cmp_gt_u32 s68, 12
	s_cselect_b32 s2, s3, s2
	s_cmp_eq_u32 s68, 13
	s_cbranch_scc1 .Ltopk_early
	s_or_b32 s3, s2, 0x100000
	v_cmp_le_u32_e64 s[66:67], s3, v5
	v_cmp_le_u32_e64 s[70:71], s3, v4
	v_cmp_le_u32_e64 s[72:73], s3, v6
	v_cmp_le_u32_e64 s[74:75], s3, v7
	s_bcnt1_i32_b64 s68, s[66:67]
	s_bcnt1_i32_b64 s66, s[70:71]
	s_add_i32 s68, s66, s68
	s_bcnt1_i32_b64 s66, s[72:73]
	s_add_i32 s68, s68, s66
	s_bcnt1_i32_b64 s66, s[74:75]
	s_add_i32 s68, s68, s66
	s_cmp_gt_u32 s68, 12
	s_cselect_b32 s2, s3, s2
	s_cmp_eq_u32 s68, 13
	s_cbranch_scc1 .Ltopk_early
	s_or_b32 s3, s2, 0x80000
	v_cmp_le_u32_e64 s[66:67], s3, v5
	v_cmp_le_u32_e64 s[70:71], s3, v4
	v_cmp_le_u32_e64 s[72:73], s3, v6
	v_cmp_le_u32_e64 s[74:75], s3, v7
	s_bcnt1_i32_b64 s68, s[66:67]
	s_bcnt1_i32_b64 s66, s[70:71]
	s_add_i32 s68, s66, s68
	s_bcnt1_i32_b64 s66, s[72:73]
	s_add_i32 s68, s68, s66
	s_bcnt1_i32_b64 s66, s[74:75]
	s_add_i32 s68, s68, s66
	s_cmp_gt_u32 s68, 12
	s_cselect_b32 s2, s3, s2
	s_cmp_eq_u32 s68, 13
	s_cbranch_scc1 .Ltopk_early
	s_or_b32 s3, s2, 0x40000
	v_cmp_le_u32_e64 s[66:67], s3, v5
	v_cmp_le_u32_e64 s[70:71], s3, v4
	v_cmp_le_u32_e64 s[72:73], s3, v6
	v_cmp_le_u32_e64 s[74:75], s3, v7
	s_bcnt1_i32_b64 s68, s[66:67]
	s_bcnt1_i32_b64 s66, s[70:71]
	s_add_i32 s68, s66, s68
	s_bcnt1_i32_b64 s66, s[72:73]
	s_add_i32 s68, s68, s66
	s_bcnt1_i32_b64 s66, s[74:75]
	s_add_i32 s68, s68, s66
	s_cmp_gt_u32 s68, 12
	s_cselect_b32 s2, s3, s2
	s_cmp_eq_u32 s68, 13
	s_cbranch_scc1 .Ltopk_early
	s_or_b32 s3, s2, 0x20000
	v_cmp_le_u32_e64 s[66:67], s3, v5
	v_cmp_le_u32_e64 s[70:71], s3, v4
	v_cmp_le_u32_e64 s[72:73], s3, v6
	v_cmp_le_u32_e64 s[74:75], s3, v7
	s_bcnt1_i32_b64 s68, s[66:67]
	s_bcnt1_i32_b64 s66, s[70:71]
	s_add_i32 s68, s66, s68
	s_bcnt1_i32_b64 s66, s[72:73]
	s_add_i32 s68, s68, s66
	s_bcnt1_i32_b64 s66, s[74:75]
	s_add_i32 s68, s68, s66
	s_cmp_gt_u32 s68, 12
	s_cselect_b32 s2, s3, s2
	s_cmp_eq_u32 s68, 13
	s_cbranch_scc1 .Ltopk_early
	s_or_b32 s3, s2, 0x10000
	v_cmp_le_u32_e64 s[66:67], s3, v5
	v_cmp_le_u32_e64 s[70:71], s3, v4
	v_cmp_le_u32_e64 s[72:73], s3, v6
	v_cmp_le_u32_e64 s[74:75], s3, v7
	s_bcnt1_i32_b64 s68, s[66:67]
	s_bcnt1_i32_b64 s66, s[70:71]
	s_add_i32 s68, s66, s68
	s_bcnt1_i32_b64 s66, s[72:73]
	s_add_i32 s68, s68, s66
	s_bcnt1_i32_b64 s66, s[74:75]
	s_add_i32 s68, s68, s66
	s_cmp_gt_u32 s68, 12
	s_cselect_b32 s2, s3, s2
	s_cmp_eq_u32 s68, 13
	s_cbranch_scc1 .Ltopk_early
	s_or_b32 s3, s2, 0x8000
	v_cmp_le_u32_e64 s[66:67], s3, v5
	v_cmp_le_u32_e64 s[70:71], s3, v4
	v_cmp_le_u32_e64 s[72:73], s3, v6
	v_cmp_le_u32_e64 s[74:75], s3, v7
	s_bcnt1_i32_b64 s68, s[66:67]
	s_bcnt1_i32_b64 s66, s[70:71]
	s_add_i32 s68, s66, s68
	s_bcnt1_i32_b64 s66, s[72:73]
	s_add_i32 s68, s68, s66
	s_bcnt1_i32_b64 s66, s[74:75]
	s_add_i32 s68, s68, s66
	s_cmp_gt_u32 s68, 12
	s_cselect_b32 s2, s3, s2
	s_cmp_eq_u32 s68, 13
	s_cbranch_scc1 .Ltopk_early
	s_or_b32 s3, s2, 0x4000
	v_cmp_le_u32_e64 s[66:67], s3, v5
	v_cmp_le_u32_e64 s[70:71], s3, v4
	v_cmp_le_u32_e64 s[72:73], s3, v6
	v_cmp_le_u32_e64 s[74:75], s3, v7
	s_bcnt1_i32_b64 s68, s[66:67]
	s_bcnt1_i32_b64 s66, s[70:71]
	s_add_i32 s68, s66, s68
	s_bcnt1_i32_b64 s66, s[72:73]
	s_add_i32 s68, s68, s66
	s_bcnt1_i32_b64 s66, s[74:75]
	s_add_i32 s68, s68, s66
	s_cmp_gt_u32 s68, 12
	s_cselect_b32 s2, s3, s2
	s_cmp_eq_u32 s68, 13
	s_cbranch_scc1 .Ltopk_early
	s_or_b32 s3, s2, 0x2000
	v_cmp_le_u32_e64 s[66:67], s3, v5
	v_cmp_le_u32_e64 s[70:71], s3, v4
	v_cmp_le_u32_e64 s[72:73], s3, v6
	v_cmp_le_u32_e64 s[74:75], s3, v7
	s_bcnt1_i32_b64 s68, s[66:67]
	s_bcnt1_i32_b64 s66, s[70:71]
	s_add_i32 s68, s66, s68
	s_bcnt1_i32_b64 s66, s[72:73]
	s_add_i32 s68, s68, s66
	s_bcnt1_i32_b64 s66, s[74:75]
	s_add_i32 s68, s68, s66
	s_cmp_gt_u32 s68, 12
	s_cselect_b32 s2, s3, s2
	s_cmp_eq_u32 s68, 13
	s_cbranch_scc1 .Ltopk_early
	s_or_b32 s3, s2, 0x1000
	v_cmp_le_u32_e64 s[66:67], s3, v5
	v_cmp_le_u32_e64 s[70:71], s3, v4
	v_cmp_le_u32_e64 s[72:73], s3, v6
	v_cmp_le_u32_e64 s[74:75], s3, v7
	s_bcnt1_i32_b64 s68, s[66:67]
	s_bcnt1_i32_b64 s66, s[70:71]
	s_add_i32 s68, s66, s68
	s_bcnt1_i32_b64 s66, s[72:73]
	s_add_i32 s68, s68, s66
	s_bcnt1_i32_b64 s66, s[74:75]
	s_add_i32 s68, s68, s66
	s_cmp_gt_u32 s68, 12
	s_cselect_b32 s2, s3, s2
	s_cmp_eq_u32 s68, 13
	s_cbranch_scc1 .Ltopk_early
	s_or_b32 s3, s2, 0x800
	v_cmp_le_u32_e64 s[66:67], s3, v5
	v_cmp_le_u32_e64 s[70:71], s3, v4
	v_cmp_le_u32_e64 s[72:73], s3, v6
	v_cmp_le_u32_e64 s[74:75], s3, v7
	s_bcnt1_i32_b64 s68, s[66:67]
	s_bcnt1_i32_b64 s66, s[70:71]
	s_add_i32 s68, s66, s68
	s_bcnt1_i32_b64 s66, s[72:73]
	s_add_i32 s68, s68, s66
	s_bcnt1_i32_b64 s66, s[74:75]
	s_add_i32 s68, s68, s66
	s_cmp_gt_u32 s68, 12
	s_cselect_b32 s2, s3, s2
	s_cmp_eq_u32 s68, 13
	s_cbranch_scc1 .Ltopk_early
	s_or_b32 s3, s2, 0x400
	v_cmp_le_u32_e64 s[66:67], s3, v5
	v_cmp_le_u32_e64 s[70:71], s3, v4
	v_cmp_le_u32_e64 s[72:73], s3, v6
	v_cmp_le_u32_e64 s[74:75], s3, v7
	s_bcnt1_i32_b64 s68, s[66:67]
	s_bcnt1_i32_b64 s66, s[70:71]
	s_add_i32 s68, s66, s68
	s_bcnt1_i32_b64 s66, s[72:73]
	s_add_i32 s68, s68, s66
	s_bcnt1_i32_b64 s66, s[74:75]
	s_add_i32 s68, s68, s66
	s_cmp_gt_u32 s68, 12
	s_cselect_b32 s2, s3, s2
	s_cmp_eq_u32 s68, 13
	s_cbranch_scc1 .Ltopk_early
	s_or_b32 s3, s2, 0x200
	v_cmp_le_u32_e64 s[66:67], s3, v5
	v_cmp_le_u32_e64 s[70:71], s3, v4
	v_cmp_le_u32_e64 s[72:73], s3, v6
	v_cmp_le_u32_e64 s[74:75], s3, v7
	s_bcnt1_i32_b64 s68, s[66:67]
	s_bcnt1_i32_b64 s66, s[70:71]
	s_add_i32 s68, s66, s68
	s_bcnt1_i32_b64 s66, s[72:73]
	s_add_i32 s68, s68, s66
	s_bcnt1_i32_b64 s66, s[74:75]
	s_add_i32 s68, s68, s66
	s_cmp_gt_u32 s68, 12
	s_cselect_b32 s2, s3, s2
	s_cmp_eq_u32 s68, 13
	s_cbranch_scc1 .Ltopk_early
	s_or_b32 s3, s2, 0x100
	v_cmp_le_u32_e64 s[66:67], s3, v5
	v_cmp_le_u32_e64 s[70:71], s3, v4
	v_cmp_le_u32_e64 s[72:73], s3, v6
	v_cmp_le_u32_e64 s[74:75], s3, v7
	s_bcnt1_i32_b64 s68, s[66:67]
	s_bcnt1_i32_b64 s66, s[70:71]
	s_add_i32 s68, s66, s68
	s_bcnt1_i32_b64 s66, s[72:73]
	s_add_i32 s68, s68, s66
	s_bcnt1_i32_b64 s66, s[74:75]
	s_add_i32 s68, s68, s66
	s_cmp_gt_u32 s68, 12
	s_cselect_b32 s2, s3, s2
	s_cmp_eq_u32 s68, 13
	s_cbranch_scc1 .Ltopk_early
	s_or_b32 s3, s2, 0x80
	v_cmp_le_u32_e64 s[66:67], s3, v5
	v_cmp_le_u32_e64 s[70:71], s3, v4
	v_cmp_le_u32_e64 s[72:73], s3, v6
	v_cmp_le_u32_e64 s[74:75], s3, v7
	s_bcnt1_i32_b64 s68, s[66:67]
	s_bcnt1_i32_b64 s66, s[70:71]
	s_add_i32 s68, s66, s68
	s_bcnt1_i32_b64 s66, s[72:73]
	s_add_i32 s68, s68, s66
	s_bcnt1_i32_b64 s66, s[74:75]
	s_add_i32 s68, s68, s66
	s_cmp_gt_u32 s68, 12
	s_cselect_b32 s2, s3, s2
	s_cmp_eq_u32 s68, 13
	s_cbranch_scc1 .Ltopk_early
	s_or_b32 s3, s2, 64
	v_cmp_le_u32_e64 s[66:67], s3, v5
	v_cmp_le_u32_e64 s[70:71], s3, v4
	v_cmp_le_u32_e64 s[72:73], s3, v6
	v_cmp_le_u32_e64 s[74:75], s3, v7
	s_bcnt1_i32_b64 s68, s[66:67]
	s_bcnt1_i32_b64 s66, s[70:71]
	s_add_i32 s68, s66, s68
	s_bcnt1_i32_b64 s66, s[72:73]
	s_add_i32 s68, s68, s66
	s_bcnt1_i32_b64 s66, s[74:75]
	s_add_i32 s68, s68, s66
	s_cmp_gt_u32 s68, 12
	s_cselect_b32 s2, s3, s2
	s_cmp_eq_u32 s68, 13
	s_cbranch_scc1 .Ltopk_early
	s_or_b32 s3, s2, 32
	v_cmp_le_u32_e64 s[66:67], s3, v5
	v_cmp_le_u32_e64 s[70:71], s3, v4
	v_cmp_le_u32_e64 s[72:73], s3, v6
	v_cmp_le_u32_e64 s[74:75], s3, v7
	s_bcnt1_i32_b64 s68, s[66:67]
	s_bcnt1_i32_b64 s66, s[70:71]
	s_add_i32 s68, s66, s68
	s_bcnt1_i32_b64 s66, s[72:73]
	s_add_i32 s68, s68, s66
	s_bcnt1_i32_b64 s66, s[74:75]
	s_add_i32 s68, s68, s66
	s_cmp_gt_u32 s68, 12
	s_cselect_b32 s2, s3, s2
	s_cmp_eq_u32 s68, 13
	s_cbranch_scc1 .Ltopk_early
	s_or_b32 s3, s2, 16
	v_cmp_le_u32_e64 s[66:67], s3, v5
	v_cmp_le_u32_e64 s[70:71], s3, v4
	v_cmp_le_u32_e64 s[72:73], s3, v6
	v_cmp_le_u32_e64 s[74:75], s3, v7
	s_bcnt1_i32_b64 s68, s[66:67]
	s_bcnt1_i32_b64 s66, s[70:71]
	s_add_i32 s68, s66, s68
	s_bcnt1_i32_b64 s66, s[72:73]
	s_add_i32 s68, s68, s66
	s_bcnt1_i32_b64 s66, s[74:75]
	s_add_i32 s68, s68, s66
	s_cmp_gt_u32 s68, 12
	s_cselect_b32 s2, s3, s2
	s_cmp_eq_u32 s68, 13
	s_cbranch_scc1 .Ltopk_early
	s_or_b32 s3, s2, 8
	v_cmp_le_u32_e64 s[66:67], s3, v5
	v_cmp_le_u32_e64 s[70:71], s3, v4
	v_cmp_le_u32_e64 s[72:73], s3, v6
	v_cmp_le_u32_e64 s[74:75], s3, v7
	s_bcnt1_i32_b64 s68, s[66:67]
	s_bcnt1_i32_b64 s66, s[70:71]
	s_add_i32 s68, s66, s68
	s_bcnt1_i32_b64 s66, s[72:73]
	s_add_i32 s68, s68, s66
	s_bcnt1_i32_b64 s66, s[74:75]
	s_add_i32 s68, s68, s66
	s_cmp_gt_u32 s68, 12
	s_cselect_b32 s2, s3, s2
	s_cmp_eq_u32 s68, 13
	s_cbranch_scc1 .Ltopk_early
	s_or_b32 s3, s2, 4
	v_cmp_le_u32_e64 s[66:67], s3, v5
	v_cmp_le_u32_e64 s[70:71], s3, v4
	v_cmp_le_u32_e64 s[72:73], s3, v6
	v_cmp_le_u32_e64 s[74:75], s3, v7
	s_bcnt1_i32_b64 s68, s[66:67]
	s_bcnt1_i32_b64 s66, s[70:71]
	s_add_i32 s68, s66, s68
	s_bcnt1_i32_b64 s66, s[72:73]
	s_add_i32 s68, s68, s66
	s_bcnt1_i32_b64 s66, s[74:75]
	s_add_i32 s68, s68, s66
	s_cmp_gt_u32 s68, 12
	s_cselect_b32 s2, s3, s2
	s_cmp_eq_u32 s68, 13
	s_cbranch_scc1 .Ltopk_early
	s_or_b32 s3, s2, 2
	v_cmp_le_u32_e64 s[66:67], s3, v5
	v_cmp_le_u32_e64 s[70:71], s3, v4
	v_cmp_le_u32_e64 s[72:73], s3, v6
	v_cmp_le_u32_e64 s[74:75], s3, v7
	s_bcnt1_i32_b64 s68, s[66:67]
	s_bcnt1_i32_b64 s66, s[70:71]
	s_add_i32 s68, s66, s68
	s_bcnt1_i32_b64 s66, s[72:73]
	s_add_i32 s68, s68, s66
	s_bcnt1_i32_b64 s66, s[74:75]
	s_add_i32 s68, s68, s66
	s_cmp_gt_u32 s68, 12
	s_cselect_b32 s2, s3, s2
	s_cmp_eq_u32 s68, 13
	s_cbranch_scc1 .Ltopk_early
	s_or_b32 s3, s2, 1
	v_cmp_le_u32_e64 s[66:67], s3, v5
	v_cmp_le_u32_e64 s[70:71], s3, v4
	v_cmp_le_u32_e64 s[72:73], s3, v6
	v_cmp_le_u32_e64 s[74:75], s3, v7
	s_bcnt1_i32_b64 s68, s[66:67]
	s_bcnt1_i32_b64 s66, s[70:71]
	s_add_i32 s68, s66, s68
	s_bcnt1_i32_b64 s66, s[72:73]
	s_add_i32 s68, s68, s66
	s_bcnt1_i32_b64 s66, s[74:75]
	s_add_i32 s68, s68, s66
	s_cmp_gt_u32 s68, 12
	s_cselect_b32 s2, s3, s2
